# GLA chunk staging: thread-to-piece mapping changed so every wave writes a contiguous 1 KB run of the same LDS image (bank-conflict-free ds_write_b128)
# baseline (speedup 1.0000x reference)
; #define LAS __attribute__((address_space(3)))
; __device__ __forceinline__ unsigned cvtpk(float lo, float hi) { f32x2 v = {lo, hi}; bf16x2_t b = __builtin_convertvector(v, bf16x2_t); return __builtin_bit_cast(unsigned, b); }
; __device__ __forceinline__ void gla_unit(LAS char* lds0, int b, int h, int dvh, bf16_t* Z, bf16_t* OT, const float* afw, const float* afb, const float* abw, const float* abb, bool dry) {
;     int tid = threadIdx.x; asm volatile("" : "+v"(tid)); const int lane = tid & 63, r32 = lane & 31, hi = lane >> 5; const int wid = __builtin_amdgcn_readfirstlane(tid >> 6);
;     const int dir = wid >> 2, wg = wid & 3, tg = tid & 255;
;     LAS char* lds = lds0 + dir * G_GROUP;
;     const int g16 = (lane >> 4) & 1, q4 = (lane & 15) >> 2, p4 = lane & 3;
;     const int I = wg >> 1, J = wg & 1;
;     const float* w2 = dir ? abw : afw; const float* bb = dir ? abb : afb;
;     bf16x8 w2b;
;     { u32x4 t; t.x = cvtpk(w2[(8 * hi + 0) * 256 + h * 64 + 32 * J + r32], w2[(8 * hi + 1) * 256 + h * 64 + 32 * J + r32]);
;       t.y = cvtpk(w2[(8 * hi + 2) * 256 + h * 64 + 32 * J + r32], w2[(8 * hi + 3) * 256 + h * 64 + 32 * J + r32]);
;       t.z = cvtpk(w2[(8 * hi + 4) * 256 + h * 64 + 32 * J + r32], w2[(8 * hi + 5) * 256 + h * 64 + 32 * J + r32]);
;       t.w = cvtpk(w2[(8 * hi + 6) * 256 + h * 64 + 32 * J + r32], w2[(8 * hi + 7) * 256 + h * 64 + 32 * J + r32]);
;       w2b = __builtin_bit_cast(bf16x8, t); }
;     const float bias = bb[h * 64 + 32 * J + r32];
;     const int zcol_a = dir ? ZAB : ZAF;
;     f32x16 S = {};
;     for (int i = tg; i < GARR / 4; i += 256) ((LAS unsigned*)(lds + G_SB))[i] = 0u;
;     u32x4 pq0, pq1, pk0, pk1, pv0, pv1; u32x2 pa;
;     const int lr = tg >> 3, lc = tg & 7, ar = tg >> 2, ac = tg & 3;
;     ...
;     GLA_PREFETCH(0);
.LBB0_401:
	v_mov_b32_e32 v6, v182
	s_bfe_u32 s8, s97, 0x20001
	v_readfirstlane_b32 s28, v6
	s_lshr_b32 s0, s28, 8
	s_mul_i32 s0, s0, 0x10a00
	s_add_i32 s76, s0, 0
	s_bfe_u32 s42, s28, 0x10006
	s_cmpk_lt_u32 s28, 0x100
	s_cselect_b64 s[0:1], -1, 0
	s_cmpk_gt_u32 s28, 0xff
	v_readlane_b32 s52, v254, 59
	s_cselect_b64 s[16:17], -1, 0
	s_and_b64 s[2:3], s[0:1], exec
	v_readlane_b32 s54, v254, 61
	v_readlane_b32 s58, v255, 1
	v_readlane_b32 s55, v254, 62
	v_readlane_b32 s59, v255, 2
	s_cselect_b32 s2, s54, s58
	s_cselect_b32 s3, s55, s59
	s_add_u32 s2, s2, s94
	s_addc_u32 s3, s3, s95
	v_readlane_b32 s56, v254, 63
	s_and_b64 s[14:15], s[0:1], exec
	v_readlane_b32 s44, v254, 55
	v_readlane_b32 s57, v255, 0
	v_readlane_b32 s45, v254, 56
	s_cselect_b32 s15, s56, s44
	v_readlane_b32 s24, v255, 36
	v_bfe_u32 v16, v6, 3, 5
	s_cselect_b32 s14, s57, s45
	v_readlane_b32 s25, v255, 37
	s_add_u32 s24, s15, s24
	v_and_b32_e32 v14, 31, v6
	v_bfe_u32 v15, v6, 5, 1
	v_xor_b32_e32 v0, 63, v16
	s_addc_u32 s25, s14, s25
	s_lshl_b32 s43, s42, 5
	v_cndmask_b32_e64 v114, v0, v16, s[0:1]
	v_lshlrev_b32_e32 v0, 11, v15
	s_lshl_b32 s77, s8, 6
	v_or_b32_e32 v18, s43, v14
	v_or3_b32 v0, v0, s77, v18
	v_lshlrev_b32_e32 v0, 2, v0
	v_lshl_add_u64 v[2:3], s[2:3], 0, v[0:1]
	global_load_dword v17, v0, s[2:3]
	global_load_dword v19, v0, s[2:3] offset:1024
	global_load_dword v21, v0, s[2:3] offset:2048
	s_nop 0
	global_load_dword v0, v0, s[2:3] offset:3072
	s_movk_i32 s2, 0x1000
	v_add_co_u32_e32 v2, vcc, s2, v2
	s_ashr_i32 s2, s97, 3
	s_nop 0
	v_addc_co_u32_e32 v3, vcc, 0, v3, vcc
	s_lshr_b32 s40, s28, 7
	s_bfe_u32 s84, s28, 0x10007
	global_load_dword v22, v[2:3], off
	global_load_dword v23, v[2:3], off offset:1024
	global_load_dword v24, v[2:3], off offset:2048
	s_nop 0
	global_load_dword v3, v[2:3], off offset:3072
	v_and_b32_e32 v2, 0xff, v6
	s_and_b64 s[14:15], s[0:1], exec
	v_lshrrev_b32_e32 v25, 5, v6
	v_bfe_u32 v26, v6, 2, 2
	v_and_b32_e32 v27, 16, v6
	v_and_b32_e32 v28, 3, v6
	v_and_b32_e32 v7, 7, v6
	v_bfe_u32 v29, v6, 2, 6
	v_xor_b32_e32 v6, 31, v16
	v_or_b32_e32 v8, 32, v16
	v_lshl_add_u32 v2, v2, 2, s76
	s_mul_hi_i32 s14, s2, 0x900
	s_mul_i32 s15, s2, 0x900
	s_movk_i32 s2, 0x380
	s_cselect_b32 s34, 0, 0xc0
	ds_write2st64_b32 v2, v1, v1 offset0:180 offset1:184
	ds_write2st64_b32 v2, v1, v1 offset0:188 offset1:192
	ds_write2st64_b32 v2, v1, v1 offset0:196 offset1:200
	ds_write2st64_b32 v2, v1, v1 offset0:204 offset1:208
	ds_write_b32 v2, v1 offset:54272
	v_cndmask_b32_e64 v118, v6, v8, s[0:1]
	v_or_b32_e32 v2, s77, v18
	s_cselect_b32 s28, s2, 0x3a0
	s_or_b32 s34, s34, s15
	v_mov_b64_e32 v[4:5], s[88:89]
	v_lshlrev_b32_e32 v2, 2, v2
	v_or_b32_e32 v6, s34, v114
	v_or_b32_e32 v8, s34, v118
	v_lshlrev_b32_e32 v20, 3, v7
	v_lshlrev_b32_e32 v116, 4, v7
	global_load_dword v2, v2, s[24:25]
	v_mad_u64_u32 v[6:7], s[24:25], v6, s13, v[4:5]
	v_mad_u64_u32 v[8:9], s[24:25], v8, s13, v[4:5]
	s_mov_b32 s3, s9
	s_lshl_b32 s2, s8, 7
	v_mad_i32_i24 v7, s14, v204, v7
	v_mad_i32_i24 v9, s14, v204, v9
	v_lshl_add_u64 v[10:11], v[6:7], 0, s[2:3]
	v_lshl_add_u64 v[12:13], v[8:9], 0, s[2:3]
	s_lshl_b32 s3, s97, 6
	s_lshl_b32 s8, s8, 8
	s_and_b32 s3, s3, 64
	s_mov_b32 s29, 0
	v_lshl_add_u64 v[6:7], v[6:7], 0, s[8:9]
	s_lshl_b32 s24, s3, 1
	s_mov_b32 s25, s9
	v_mov_b32_e32 v117, v1
	v_lshl_add_u64 v[6:7], v[6:7], 0, s[24:25]
	v_lshl_add_u64 v[8:9], v[8:9], 0, s[8:9]
	v_lshl_add_u64 v[10:11], v[10:11], 0, v[116:117]
	v_lshl_add_u64 v[12:13], v[12:13], 0, v[116:117]
	v_lshl_add_u64 v[6:7], v[6:7], 0, v[116:117]
	v_lshl_add_u64 v[8:9], v[8:9], 0, s[24:25]
	global_load_dwordx4 v[70:73], v[10:11], off offset:2048
	global_load_dwordx4 v[74:77], v[10:11], off offset:2560
	global_load_dwordx4 v[78:81], v[12:13], off offset:2048
	global_load_dwordx4 v[82:85], v[12:13], off offset:2560
	v_lshl_add_u64 v[8:9], v[8:9], 0, v[116:117]
	global_load_dwordx4 v[86:89], v[6:7], off offset:3072
	global_load_dwordx4 v[90:93], v[8:9], off offset:3072
	v_and_b32_e32 v6, 64, v203
	v_add_u32_e32 v6, 64, v6
	v_lshlrev_b32_e32 v30, 3, v15
	v_mov_b32_e32 v31, s76
	s_movk_i32 s44, 0x90
	v_mad_u32_u24 v136, v18, s44, v31
	v_or_b32_e32 v44, v30, v26
	v_readlane_b32 s46, v254, 57
	v_readlane_b32 s47, v254, 58
	v_mul_u32_u24_e32 v154, 0x90, v44
	v_or_b32_e32 v44, 16, v30
	v_or_b32_e32 v46, 32, v30
	v_or_b32_e32 v30, 48, v30
	v_readlane_b32 s53, v254, 60
	v_mad_u32_u24 v115, v16, s44, v31
	s_or_b32 s18, s84, s42
	v_and_b32_e32 v244, 0xff, v182
	v_lshl_add_u32 v241, v244, 4, v31
	v_mov_b32_e32 v247, v244
	v_mul_u32_u24_e32 v245, 0x1c72, v247
	v_lshrrev_b32_e32 v245, 16, v245
	v_mul_u32_u24_e32 v246, 9, v245
	v_sub_u32_e32 v246, v247, v246
	v_cmp_eq_u32_e32 vcc, 8, v246
	v_cndmask_b32_e64 v246, v246, 0, vcc
	v_lshlrev_b32_e32 v200, 4, v246
	v_mov_b32_e32 v201, 0
	v_xor_b32_e32 v246, 63, v245
	v_cndmask_b32_e64 v184, v246, v245, s[0:1]
	v_add_u32_e32 v247, 0x100, v244
	v_mul_u32_u24_e32 v245, 0x1c72, v247
	v_lshrrev_b32_e32 v245, 16, v245
	v_mul_u32_u24_e32 v246, 9, v245
	v_sub_u32_e32 v246, v247, v246
	v_cmp_eq_u32_e32 vcc, 8, v246
	v_cndmask_b32_e64 v246, v246, 0, vcc
	v_lshlrev_b32_e32 v248, 4, v246
	v_mov_b32_e32 v249, 0
	v_xor_b32_e32 v246, 63, v245
	v_cndmask_b32_e64 v185, v246, v245, s[0:1]
	v_add_u32_e32 v247, 0x200, v244
	v_mul_u32_u24_e32 v245, 0x1c72, v247
	v_lshrrev_b32_e32 v245, 16, v245
	v_mul_u32_u24_e32 v246, 9, v245
	v_sub_u32_e32 v246, v247, v246
	v_cmp_eq_u32_e32 vcc, 8, v246
	v_cndmask_b32_e64 v246, v246, 0, vcc
	v_lshlrev_b32_e32 v250, 4, v246
	v_mov_b32_e32 v251, 0
	v_xor_b32_e32 v246, 63, v245
	v_cndmask_b32_e64 v205, v246, v245, s[0:1]
	s_waitcnt vmcnt(0)
; __device__ __forceinline__ void gla_unit(LAS char* lds0, int b, int h, int dvh, bf16_t* Z, bf16_t* OT, const float* afw, const float* afb, const float* abw, const float* abb, bool dry) {
;     ...
;     f32x16 S = {};
;     for (int i = tg; i < GARR / 4; i += 256) ((LAS unsigned*)(lds + G_SB))[i] = 0u;
;     u32x4 pq0, pq1, pk0, pk1, pv0, pv1; u32x2 pa;
;     const int lr = tg >> 3, lc = tg & 7, ar = tg >> 2, ac = tg & 3;
;     ...
;     GLA_PREFETCH(0);
;     for (int s = 0; s < 36; ++s) {
;         const int c = GLA_CHUNK(s);
;         const size_t rbase = (size_t)b * TOK + 64 * c;
;         const int other_step = dir ? c : (c < 4 ? 3 - c : 39 - c);
;         const bool second = s > other_step;
;         *(LAS u32x4*)(lds + G_Q + lr * GP + lc * 16) = pq0; *(LAS u32x4*)(lds + G_Q + (lr + 32) * GP + lc * 16) = pq1;
;         *(LAS u32x4*)(lds + G_K + lr * GP + lc * 16) = pk0; *(LAS u32x4*)(lds + G_K + (lr + 32) * GP + lc * 16) = pk1;
;         *(LAS u32x4*)(lds + G_V + lr * GP + lc * 16) = pv0; *(LAS u32x4*)(lds + G_V + (lr + 32) * GP + lc * 16) = pv1;
;         *(LAS u32x2*)(lds + G_A16 + ar * 32 + ac * 8) = pa;
;         __syncthreads();
;         if (s + 1 < 36) GLA_PREFETCH(s + 1);
;         u32x4 prv0 = {0u, 0u, 0u, 0u}, prv1 = {0u, 0u, 0u, 0u};
;         bf16_t* og0 = OT + GLA_ROW(rbase, lr) * 512 + h * 128 + dvh * 64 + lc * 8;
;         bf16_t* og1 = OT + GLA_ROW(rbase, lr + 32) * 512 + h * 128 + dvh * 64 + lc * 8;
;         if (second) { prv0 = *(const u32x4*)og0; prv1 = *(const u32x4*)og1; }
;         float cs[16];
;         {
;             f32x16 zc;
; #pragma unroll
;             for (int r = 0; r < 16; ++r) zc[r] = bias;
;             const bf16x8 a = *(const LAS bf16x8*)(lds + G_A16 + (32 * I + r32) * 32 + hi * 16);
;             zc = __builtin_amdgcn_mfma_f32_32x32x16_bf16(a, w2b, zc, 0, 0, 0);
; #pragma unroll
;             for (int r = 0; r < 16; ++r) { const float z = zc[r]; cs[r] = (fminf(z, 0.f) - __logf(1.f + fexp(-fabsf(z)))) * (1.f / 16.f); }
;         }
; #pragma unroll
;         for (int g = 0; g < 4; ++g) { cs[4 * g + 1] += cs[4 * g]; cs[4 * g + 2] += cs[4 * g + 1]; cs[4 * g + 3] += cs[4 * g + 2]; }
;         float run = 0.f;
; #pragma unroll
;         for (int g = 0; g < 4; ++g) {
;             const float mine = cs[4 * g + 3]; const float oth = __shfl_xor(mine, 32);
;             const float off = run + (hi ? oth : 0.f);
; #pragma unroll
	v_cvt_pk_bf16_f32 v67, v21, v0
	v_xor_b32_e32 v0, 63, v29
	v_cndmask_b32_e64 v120, v0, v29, s[0:1]
	v_or_b32_e32 v0, s34, v120
	v_mad_u64_u32 v[4:5], s[34:35], v0, s13, v[4:5]
	v_mad_i32_i24 v5, s14, v204, v5
	v_lshl_add_u64 v[4:5], v[4:5], 0, s[28:29]
	v_lshlrev_b32_e32 v0, 3, v28
	v_lshl_add_u64 v[4:5], v[4:5], 0, v[0:1]
	global_load_dwordx2 v[126:127], v[4:5], off
	s_add_u32 s34, s88, s28
	s_addc_u32 s35, s89, 0
	v_lshl_add_u64 v[122:123], s[34:35], 0, v[0:1]
	v_readlane_b32 s34, v252, 21
	v_readlane_b32 s35, v252, 22
	s_add_u32 s8, s34, s8
	s_addc_u32 s25, s35, 0
	s_add_u32 s24, s8, s24
	s_addc_u32 s25, s25, 0
	v_lshl_add_u64 v[124:125], s[24:25], 0, v[116:117]
	s_add_i32 s24, s76, 0x10500
	s_lshl_b32 s28, s42, 7
	v_xor_b32_e32 v5, 32, v203
	s_lshl_b32 s25, s84, 8
	s_add_i32 s28, s24, s28
	s_lshl_b32 s8, s84, 5
	v_cmp_lt_i32_e32 vcc, v5, v6
	s_add_i32 s25, s28, s25
	v_cvt_pk_bf16_f32 v68, v22, v23
	v_cndmask_b32_e32 v5, v203, v5, vcc
	v_lshlrev_b32_e32 v6, 2, v18
	s_cmp_eq_u32 s84, 0
	v_lshl_or_b32 v23, v15, 2, s8
	v_lshl_add_u32 v21, v29, 5, s76
	v_lshlrev_b32_e32 v119, 2, v5
	v_lshlrev_b32_e32 v5, 2, v14
	v_add_u32_e32 v132, s24, v6
	s_cselect_b64 s[34:35], -1, 0
	s_add_i32 s24, s76, 0x10400
	v_mul_u32_u24_e32 v29, 0x48, v23
	v_cvt_pk_bf16_f32 v69, v24, v3
	v_lshlrev_b32_e32 v3, 2, v28
	v_or_b32_e32 v4, s8, v14
	v_add_u32_e32 v121, s25, v5
	v_lshlrev_b32_e32 v24, 1, v18
	s_cmp_le_u32 s42, s84
	s_movk_i32 s25, 0xff72
	v_lshlrev_b32_e32 v29, 1, v29
	v_lshl_add_u32 v22, v4, 5, s76
	v_lshlrev_b32_e32 v117, 4, v15
	v_add_u32_e32 v133, s28, v5
	v_bitop3_b32 v5, s40, 1, v25 bitop3:0xc8
	s_cselect_b64 s[78:79], -1, 0
	v_mad_u32_u24 v135, v4, s44, v31
	v_or3_b32 v4, v3, v27, s43
	v_mad_i32_i24 v25, v18, s25, v136
	v_lshl_add_u32 v238, v23, 1, v136
	v_add_u32_e32 v239, v136, v117
	s_lshl_b32 s25, s42, 6
	v_or3_b32 v3, v27, s8, v3
	v_add3_u32 v138, s76, v24, v29
	v_or_b32_e32 v29, 2, v23
	s_add_i32 s8, s76, 0x10420
	v_lshl_add_u32 v137, v4, 1, s76
	s_add_i32 s25, s76, s25
	v_lshl_add_u32 v27, v3, 1, s76
	v_or_b32_e32 v24, 1, v23
	v_or_b32_e32 v31, 3, v23
	v_or_b32_e32 v32, 8, v23
	v_or_b32_e32 v33, 9, v23
	v_or_b32_e32 v34, 10, v23
	v_or_b32_e32 v35, 11, v23
	v_or_b32_e32 v36, 16, v23
	v_or_b32_e32 v37, 17, v23
	v_or_b32_e32 v38, 18, v23
	v_or_b32_e32 v39, 19, v23
	v_or_b32_e32 v40, 24, v23
	v_or_b32_e32 v41, 25, v23
	v_or_b32_e32 v42, 26, v23
	v_or_b32_e32 v43, 27, v23
	v_lshlrev_b32_e32 v45, 1, v44
	v_or_b32_e32 v44, v44, v26
	v_lshlrev_b32_e32 v47, 1, v46
	v_or_b32_e32 v46, v46, v26
	v_or_b32_e32 v26, v30, v26
	v_cmp_lt_u32_e64 s[46:47], v29, v18
	v_add_u32_e32 v29, s8, v117
	s_add_i32 s8, s76, 0x10440
	s_add_i32 s76, s76, 0x10460
	v_cvt_pk_bf16_f32 v66, v17, v19
	v_add_u32_e32 v19, 0x1200, v115
	v_lshl_add_u32 v28, v14, 1, s25
	v_mul_u32_u24_e32 v44, 0x90, v44
	v_mul_u32_u24_e32 v46, 0x90, v46
	v_lshlrev_b32_e32 v48, 1, v30
	v_mul_u32_u24_e32 v26, 0x90, v26
	v_cmp_lt_u32_e64 s[42:43], v23, v18
	v_mul_u32_u24_e32 v23, 0x90, v23
	v_cmp_lt_u32_e64 s[44:45], v24, v18
	v_cmp_lt_u32_e64 s[50:51], v31, v18
	v_cmp_lt_u32_e64 s[52:53], v32, v18
	v_cmp_lt_u32_e64 s[54:55], v33, v18
	v_cmp_lt_u32_e64 s[56:57], v34, v18
	v_cmp_lt_u32_e64 s[58:59], v35, v18
	v_cmp_lt_u32_e64 s[60:61], v36, v18
	v_cmp_lt_u32_e64 s[62:63], v37, v18
	v_cmp_lt_u32_e64 s[64:65], v38, v18
	v_cmp_lt_u32_e64 s[66:67], v39, v18
	v_cmp_lt_u32_e64 s[68:69], v40, v18
	v_cmp_lt_u32_e64 s[70:71], v41, v18
	v_cmp_lt_u32_e64 s[72:73], v42, v18
	v_cmp_lt_u32_e64 s[74:75], v43, v18
	s_lshl_b32 s25, s84, 7
	v_add_u32_e32 v24, s24, v117
	v_add_u32_e32 v30, s8, v117
	v_add_u32_e32 v31, s76, v117
	v_mov_b32_e32 v18, 0
	v_cmp_eq_u32_e64 s[38:39], 0, v15
	v_cmp_eq_u32_e64 s[40:41], 0, v5
	v_add_u32_e32 v134, s24, v6
	v_mov_b32_e32 v3, v2
	v_mov_b32_e32 v4, v2
	v_mov_b32_e32 v5, v2
	v_mov_b32_e32 v6, v2
	v_mov_b32_e32 v7, v2
	v_mov_b32_e32 v8, v2
	v_mov_b32_e32 v9, v2
	v_mov_b32_e32 v10, v2
	v_mov_b32_e32 v11, v2
	v_mov_b32_e32 v12, v2
	v_mov_b32_e32 v13, v2
	v_mov_b32_e32 v14, v2
	v_mov_b32_e32 v15, v2
	v_mov_b32_e32 v16, v2
	v_mov_b32_e32 v17, v2
	v_add_u32_e32 v139, 0x90, v138
	s_waitcnt lgkmcnt(5)
	v_add_u32_e32 v140, 0x120, v138
	v_add_u32_e32 v141, 0x1b0, v138
	v_add_u32_e32 v142, 0x480, v138
	v_add_u32_e32 v143, 0x510, v138
	v_add_u32_e32 v144, 0x5a0, v138
	v_add_u32_e32 v145, 0x630, v138
	v_add_u32_e32 v146, 0x900, v138
	v_add_u32_e32 v147, 0x990, v138
	v_add_u32_e32 v148, 0xa20, v138
	v_add_u32_e32 v149, 0xab0, v138
	v_add_u32_e32 v150, 0xd80, v138
	v_add_u32_e32 v151, 0xe10, v138
	v_add_u32_e32 v152, 0xea0, v138
	v_add_u32_e32 v153, 0xf30, v138
	v_add_u32_e32 v155, v21, v0
	s_lshl_b32 s8, s77, 1
	v_lshlrev_b32_e32 v0, 1, v20
	s_lshl_b32 s24, s2, 1
	s_lshl_b32 s84, s3, 1
	v_add_u32_e32 v156, v22, v117
	v_add_u32_e32 v157, v137, v44
	v_add_u32_e32 v158, v137, v46
	v_add_u32_e32 v159, v137, v26
	v_add_u32_e32 v160, v25, v23
	v_add_u32_e32 v161, v28, v23
	v_add_u32_e32 v162, s25, v24
	v_add_u32_e32 v163, s25, v29
	v_add_u32_e32 v164, s25, v30
	v_add_u32_e32 v165, s25, v31
	v_add_u32_e32 v166, v27, v154
	v_add_u32_e32 v167, v19, v116
	v_add_u32_e32 v168, v135, v45
	v_add_u32_e32 v169, v135, v47
	v_add_u32_e32 v170, v135, v48
	s_mov_b32 s76, s29
	v_mov_b32_e32 v19, v18
	v_mov_b32_e32 v20, v18
	v_mov_b32_e32 v21, v18
	v_mov_b32_e32 v22, v18
	v_mov_b32_e32 v23, v18
	v_mov_b32_e32 v24, v18
	v_mov_b32_e32 v25, v18
	v_mov_b32_e32 v26, v18
	v_mov_b32_e32 v27, v18
	v_mov_b32_e32 v28, v18
	v_mov_b32_e32 v29, v18
	v_mov_b32_e32 v30, v18
	v_mov_b32_e32 v31, v18
	v_mov_b32_e32 v32, v18
	v_mov_b32_e32 v33, v18
	s_branch .LBB0_403

; #define LAS __attribute__((address_space(3)))
; __device__ __forceinline__ void gla_unit(LAS char* lds0, int b, int h, int dvh, bf16_t* Z, bf16_t* OT, const float* afw, const float* afb, const float* abw, const float* abb, bool dry) {
;     ...
;         *(LAS u32x4*)(lds + G_Q + lr * GP + lc * 16) = pq0; *(LAS u32x4*)(lds + G_Q + (lr + 32) * GP + lc * 16) = pq1;
;         *(LAS u32x4*)(lds + G_K + lr * GP + lc * 16) = pk0; *(LAS u32x4*)(lds + G_K + (lr + 32) * GP + lc * 16) = pk1;
;         *(LAS u32x4*)(lds + G_V + lr * GP + lc * 16) = pv0; *(LAS u32x4*)(lds + G_V + (lr + 32) * GP + lc * 16) = pv1;
;         *(LAS u32x2*)(lds + G_A16 + ar * 32 + ac * 8) = pa;
;         __syncthreads();
.LBB0_403:
	s_add_i32 s28, s76, 1
	v_add_u32_e32 v171, v115, v116
	s_cmp_eq_u32 s76, 0
	s_cbranch_scc1 .Lg6_old
	s_waitcnt vmcnt(8)
	ds_write_b128 v241, v[70:73]
	s_waitcnt vmcnt(6)
	ds_write_b128 v241, v[78:81] offset:4096
	ds_write_b128 v241, v[74:77] offset:9216
	s_waitcnt vmcnt(5)
	ds_write_b128 v241, v[82:85] offset:13312
	s_waitcnt vmcnt(4)
	ds_write_b128 v241, v[86:89] offset:27648
	s_waitcnt vmcnt(3)
	ds_write_b128 v241, v[90:93] offset:31744
	s_waitcnt vmcnt(0)
	ds_write_b64 v155, v[126:127] offset:64512
	s_cmp_lg_u32 s18, 0
	s_cbranch_scc1 .Lg6_join
	ds_write_b128 v241, v[192:195] offset:8192
	ds_write_b128 v241, v[196:199] offset:17408
	ds_write_b128 v241, v[244:247] offset:35840
	s_branch .Lg6_join
.Lg6_old:
	s_waitcnt vmcnt(8)
	ds_write_b128 v171, v[70:73]
	s_waitcnt vmcnt(6)
	ds_write_b128 v167, v[78:81]
	ds_write_b128 v171, v[74:77] offset:9216
	s_waitcnt vmcnt(5)
	ds_write_b128 v167, v[82:85] offset:9216
	s_waitcnt vmcnt(4)
	ds_write_b128 v171, v[86:89] offset:27648
	s_waitcnt vmcnt(3)
	ds_write_b128 v167, v[90:93] offset:27648
	s_waitcnt vmcnt(0)
	ds_write_b64 v155, v[126:127] offset:64512
.Lg6_join:
	s_cmpk_eq_i32 s29, 0xffdd
	s_waitcnt lgkmcnt(0)
	s_barrier
	s_cbranch_scc1 .LBB0_410
	s_andn2_b64 vcc, exec, s[16:17]
	s_mov_b32 s25, s28
	s_cbranch_vccnz .LBB0_409
	s_cmp_gt_u32 s76, 2
	s_mov_b64 s[2:3], -1
	s_cbranch_scc0 .LBB0_407
	s_add_i32 s25, s29, 38
	s_mov_b64 s[2:3], 0

.LBB0_409:
	s_lshl_b32 s2, s25, 6
	s_add_u32 s77, s15, s2
	s_addc_u32 s25, s14, 0
	v_mov_b64_e32 v[34:35], s[88:89]
	s_mul_i32 vcc_lo, s25, 0x1c00
	s_mov_b32 s25, s9
	s_mov_b32 s85, s9
	v_or_b32_e32 v36, s77, v184
	v_mad_u64_u32 v[36:37], s[2:3], v36, s13, v[34:35]
	v_add_u32_e32 v37, vcc_lo, v37
	v_lshl_add_u64 v[38:39], v[36:37], 0, s[8:9]
	v_lshl_add_u64 v[36:37], v[36:37], 0, s[24:25]
	v_lshl_add_u64 v[36:37], v[36:37], 0, s[84:85]
	v_lshl_add_u64 v[38:39], v[38:39], 0, v[200:201]
	v_lshl_add_u64 v[36:37], v[36:37], 0, v[200:201]
	v_or_b32_e32 v40, s77, v185
	v_mad_u64_u32 v[40:41], s[2:3], v40, s13, v[34:35]
	v_add_u32_e32 v41, vcc_lo, v41
	v_lshl_add_u64 v[42:43], v[40:41], 0, s[8:9]
	v_lshl_add_u64 v[40:41], v[40:41], 0, s[24:25]
	v_lshl_add_u64 v[40:41], v[40:41], 0, s[84:85]
	v_lshl_add_u64 v[42:43], v[42:43], 0, v[248:249]
	v_lshl_add_u64 v[40:41], v[40:41], 0, v[248:249]
	global_load_dwordx4 v[70:73], v[38:39], off offset:2048
	global_load_dwordx4 v[74:77], v[38:39], off offset:2560
	global_load_dwordx4 v[78:81], v[42:43], off offset:2048
	global_load_dwordx4 v[82:85], v[42:43], off offset:2560
	global_load_dwordx4 v[86:89], v[36:37], off offset:3072
	global_load_dwordx4 v[90:93], v[40:41], off offset:3072
	s_cmp_lg_u32 s18, 0
	s_cbranch_scc1 .Lg6_nr2
	v_or_b32_e32 v44, s77, v205
	v_mad_u64_u32 v[44:45], s[2:3], v44, s13, v[34:35]
	v_add_u32_e32 v45, vcc_lo, v45
	v_lshl_add_u64 v[46:47], v[44:45], 0, s[8:9]
	v_lshl_add_u64 v[44:45], v[44:45], 0, s[24:25]
	v_lshl_add_u64 v[44:45], v[44:45], 0, s[84:85]
	v_lshl_add_u64 v[46:47], v[46:47], 0, v[250:251]
	v_lshl_add_u64 v[44:45], v[44:45], 0, v[250:251]
	global_load_dwordx4 v[192:195], v[46:47], off offset:2048
	global_load_dwordx4 v[196:199], v[46:47], off offset:2560
	global_load_dwordx4 v[244:247], v[44:45], off offset:3072
.Lg6_nr2:
	v_or_b32_e32 v34, s77, v120
	v_mad_u64_u32 v[34:35], s[2:3], v34, s13, v[122:123]
	v_add_u32_e32 v35, vcc_lo, v35
	global_load_dwordx2 v[126:127], v[34:35], off
